# sample units: SSD z values of 4 steps prefetched before step loop; HGRN sample gate loads hoisted above state stores (counted wait)
# speedup vs baseline: 1.0016x; 1.0016x over previous
.LBB0_866:
	v_lshlrev_b32_e32 v200, 2, v144
	v_mov_b32_e32 v201, v135
	s_lshl_b32 s100, s45, 8
	s_add_u32 s98, s16, s100
	s_addc_u32 s99, s17, 0
	v_lshl_add_u64 v[202:203], s[98:99], 0, v[200:201]
	s_or_b64 s[100:101], s[6:7], s[0:1]
	s_lshl_b64 s[100:101], s[100:101], 11
	v_lshl_add_u64 v[204:205], v[202:203], 0, s[100:101]
	global_load_dword v206, v[204:205], off
	s_or_b64 s[100:101], s[6:7], s[4:5]
	s_lshl_b64 s[100:101], s[100:101], 11
	v_lshl_add_u64 v[208:209], v[202:203], 0, s[100:101]
	global_load_dword v207, v[208:209], off
	s_lshl_b64 s[8:9], s[8:9], 2
	s_add_u32 s8, s14, s8
	s_addc_u32 s9, s15, s9
	v_lshlrev_b32_e32 v134, 2, v136
	v_lshl_add_u64 v[130:131], s[8:9], 0, v[134:135]
	v_lshlrev_b32_e32 v134, 2, v138
	v_lshl_add_u64 v[130:131], v[130:131], 0, v[134:135]
	global_store_dwordx4 v[130:131], v[14:17], off nt
	global_store_dwordx4 v[130:131], v[10:13], off offset:1024 nt
	global_store_dwordx4 v[130:131], v[6:9], off offset:2048 nt
	global_store_dwordx4 v[130:131], v[2:5], off offset:3072 nt
	s_lshl_b32 s34, s45, 8
	s_add_u32 s8, s16, s34
	v_add_co_u32_e32 v2, vcc, s37, v130
	s_addc_u32 s9, s17, 0
	s_nop 0
	v_addc_co_u32_e32 v3, vcc, 0, v131, vcc
	v_add_co_u32_e32 v4, vcc, s38, v130
	v_lshlrev_b32_e32 v134, 2, v144
	s_nop 0
	v_addc_co_u32_e32 v5, vcc, 0, v131, vcc
	global_store_dwordx4 v[4:5], v[78:81], off offset:-4096 nt
	global_store_dwordx4 v[2:3], v[22:25], off offset:1024 nt
	global_store_dwordx4 v[2:3], v[18:21], off offset:2048 nt
	global_store_dwordx4 v[2:3], v[86:89], off offset:3072 nt
	global_store_dwordx4 v[4:5], v[74:77], off nt
	global_store_dwordx4 v[4:5], v[70:73], off offset:1024 nt
	global_store_dwordx4 v[4:5], v[66:69], off offset:2048 nt
	global_store_dwordx4 v[4:5], v[82:85], off offset:3072 nt
	v_add_co_u32_e32 v2, vcc, s39, v130
	v_lshl_add_u64 v[6:7], s[8:9], 0, v[134:135]
	s_nop 0
	v_addc_co_u32_e32 v3, vcc, 0, v131, vcc
	v_add_co_u32_e32 v4, vcc, s40, v130
	s_add_u32 s8, s10, s34
	s_nop 0
	v_addc_co_u32_e32 v5, vcc, 0, v131, vcc
	global_store_dwordx4 v[4:5], v[34:37], off offset:-4096 nt
	global_store_dwordx4 v[2:3], v[62:65], off offset:1024 nt
	global_store_dwordx4 v[2:3], v[58:61], off offset:2048 nt
	global_store_dwordx4 v[2:3], v[54:57], off offset:3072 nt
	global_store_dwordx4 v[4:5], v[50:53], off nt
	global_store_dwordx4 v[4:5], v[46:49], off offset:1024 nt
	global_store_dwordx4 v[4:5], v[42:45], off offset:2048 nt
	global_store_dwordx4 v[4:5], v[38:41], off offset:3072 nt
	v_add_co_u32_e32 v2, vcc, s41, v130
	s_addc_u32 s9, s11, 0
	s_nop 0
	v_addc_co_u32_e32 v3, vcc, 0, v131, vcc
	v_add_co_u32_e32 v4, vcc, s25, v130
	s_or_b64 s[34:35], s[6:7], s[0:1]
	s_nop 0
	v_addc_co_u32_e32 v5, vcc, 0, v131, vcc
	global_store_dwordx4 v[4:5], v[110:113], off offset:-4096 nt
	global_store_dwordx4 v[2:3], v[30:33], off offset:1024 nt
	global_store_dwordx4 v[2:3], v[26:29], off offset:2048 nt
	global_store_dwordx4 v[2:3], v[126:129], off offset:3072 nt
	global_store_dwordx4 v[4:5], v[102:105], off nt
	global_store_dwordx4 v[4:5], v[98:101], off offset:1024 nt
	global_store_dwordx4 v[4:5], v[94:97], off offset:2048 nt
	global_store_dwordx4 v[4:5], v[90:93], off offset:3072 nt
	v_add_co_u32_e32 v2, vcc, s42, v130
	s_lshl_b64 s[34:35], s[34:35], 11
	s_nop 0
	v_addc_co_u32_e32 v3, vcc, 0, v131, vcc
	global_store_dwordx4 v[2:3], v[106:109], off nt
	global_store_dwordx4 v[2:3], v[122:125], off offset:1024 nt
	global_store_dwordx4 v[2:3], v[118:121], off offset:2048 nt
	global_store_dwordx4 v[2:3], v[114:117], off offset:3072 nt
	v_lshl_add_u64 v[2:3], v[6:7], 0, s[34:35]
	s_waitcnt lgkmcnt(0)
	s_barrier
	v_lshlrev_b32_e32 v9, 3, v144
	v_add_u32_e32 v2, s22, v9
	ds_read2st64_b64 v[2:5], v2 offset0:64 offset1:65
	v_xor_b32_e32 v10, 1, v154
	v_cmp_lt_i32_e32 vcc, v10, v156
	v_lshl_add_u64 v[12:13], s[8:9], 0, v[134:135]
	s_or_b64 s[6:7], s[6:7], s[4:5]
	s_waitcnt lgkmcnt(0)
	v_pk_add_f32 v[2:3], v[2:3], v[4:5]
	v_cndmask_b32_e32 v10, v154, v10, vcc
	v_pk_mul_f32 v[4:5], v[2:3], v[2:3]
	v_lshlrev_b32_e32 v14, 2, v10
	v_add_f32_e32 v4, v4, v5
	ds_bpermute_b32 v5, v14, v4
	v_xor_b32_e32 v10, 2, v154
	v_cmp_lt_i32_e32 vcc, v10, v156
	s_lshl_b64 s[6:7], s[6:7], 11
	s_waitcnt lgkmcnt(0)
	v_add_f32_e32 v4, v4, v5
	v_cndmask_b32_e32 v10, v154, v10, vcc
	v_lshlrev_b32_e32 v15, 2, v10
	ds_bpermute_b32 v5, v15, v4
	v_xor_b32_e32 v10, 4, v154
	v_cmp_lt_i32_e32 vcc, v10, v156
	s_waitcnt lgkmcnt(0)
	v_add_f32_e32 v4, v4, v5
	v_cndmask_b32_e32 v10, v154, v10, vcc
	v_lshlrev_b32_e32 v16, 2, v10
	ds_bpermute_b32 v5, v16, v4
	v_xor_b32_e32 v10, 8, v154
	v_cmp_lt_i32_e32 vcc, v10, v156
	s_waitcnt lgkmcnt(0)
	v_add_f32_e32 v4, v4, v5
	v_cndmask_b32_e32 v10, v154, v10, vcc
	v_lshlrev_b32_e32 v17, 2, v10
	ds_bpermute_b32 v5, v17, v4
	v_xor_b32_e32 v10, 16, v154
	v_cmp_lt_i32_e32 vcc, v10, v156
	s_waitcnt lgkmcnt(0)
	v_add_f32_e32 v4, v4, v5
	v_cndmask_b32_e32 v10, v154, v10, vcc
	v_lshlrev_b32_e32 v18, 2, v10
	ds_bpermute_b32 v5, v18, v4
	s_waitcnt lgkmcnt(0)
	v_add_f32_e32 v10, v4, v5
	ds_bpermute_b32 v11, v145, v10
	s_waitcnt vmcnt(32)
	v_lshlrev_b32_e32 v4, 16, v206
	v_and_b32_e32 v5, 0xffff0000, v206
	s_waitcnt lgkmcnt(0)
	v_add_f32_e32 v8, v10, v11
	v_mul_f32_e32 v10, 0xbfb8aa3b, v4
	v_mul_f32_e32 v11, 0xbfb8aa3b, v5
	v_exp_f32_e32 v10, v10
	v_exp_f32_e32 v11, v11
	v_fmamk_f32 v8, v8, 0x3c000000, v137
	v_rsq_f32_e32 v8, v8
	v_add_f32_e32 v10, 1.0, v10
	v_add_f32_e32 v11, 1.0, v11
	v_rcp_f32_e32 v10, v10
	v_rcp_f32_e32 v11, v11
	v_pk_mul_f32 v[2:3], v[2:3], v[8:9] op_sel_hi:[1,0]
	v_pk_mul_f32 v[4:5], v[10:11], v[4:5]
	s_nop 0
	v_pk_mul_f32 v[2:3], v[2:3], v[4:5]
	v_lshl_add_u64 v[10:11], v[12:13], 0, s[6:7]
	v_cvt_pk_bf16_f32 v4, v2, v3
	v_lshl_add_u64 v[2:3], v[12:13], 0, s[34:35]
	global_store_dword v[2:3], v4, off
	v_lshl_add_u64 v[2:3], v[6:7], 0, s[6:7]
	v_add_u32_e32 v2, s23, v9
	ds_read2st64_b64 v[2:5], v2 offset0:64 offset1:65
	s_mov_b64 s[6:7], 0
	s_waitcnt lgkmcnt(0)
	v_pk_add_f32 v[2:3], v[2:3], v[4:5]
	s_nop 0
	v_pk_mul_f32 v[4:5], v[2:3], v[2:3]
	s_nop 0
	v_add_f32_e32 v4, v4, v5
	ds_bpermute_b32 v5, v14, v4
	s_waitcnt lgkmcnt(0)
	v_add_f32_e32 v4, v4, v5
	ds_bpermute_b32 v5, v15, v4
	s_waitcnt lgkmcnt(0)
	v_add_f32_e32 v4, v4, v5
	ds_bpermute_b32 v5, v16, v4
	s_waitcnt lgkmcnt(0)
	v_add_f32_e32 v4, v4, v5
	ds_bpermute_b32 v5, v17, v4
	s_waitcnt lgkmcnt(0)
	v_add_f32_e32 v4, v4, v5
	ds_bpermute_b32 v5, v18, v4
	s_waitcnt lgkmcnt(0)
	v_add_f32_e32 v4, v4, v5
	ds_bpermute_b32 v5, v145, v4
	s_waitcnt lgkmcnt(0)
	v_add_f32_e32 v7, v4, v5
	v_lshlrev_b32_e32 v4, 16, v207
	v_and_b32_e32 v5, 0xffff0000, v207
	v_mul_f32_e32 v6, 0xbfb8aa3b, v4
	v_mul_f32_e32 v8, 0xbfb8aa3b, v5
	v_exp_f32_e32 v9, v6
	v_exp_f32_e32 v8, v8
	v_fmamk_f32 v6, v7, 0x3c000000, v137
	v_rsq_f32_e32 v6, v6
	v_add_f32_e32 v7, 1.0, v9
	v_add_f32_e32 v9, 1.0, v8
	v_rcp_f32_e32 v8, v7
	v_rcp_f32_e32 v9, v9
	v_pk_mul_f32 v[2:3], v[2:3], v[6:7] op_sel_hi:[1,0]
	v_pk_mul_f32 v[4:5], v[8:9], v[4:5]
	s_nop 0
	v_pk_mul_f32 v[2:3], v[2:3], v[4:5]
	s_nop 0
	v_cvt_pk_bf16_f32 v2, v2, v3
	global_store_dword v[10:11], v2, off
	s_barrier

.LBB0_927:
	s_or_b64 exec, exec, s[6:7]
	s_lshl_b32 s15, s14, 2
	v_mov_b32_e32 v131, s15
	s_waitcnt lgkmcnt(0)
	s_barrier
	global_load_dword v132, v131, s[78:79]
	global_load_dword v149, v131, s[80:81]
	v_and_b32_e32 v131, 16, v164
	v_cmp_eq_u32_e32 vcc, 0, v131
	v_and_b32_e32 v131, 8, v164
	v_xor_b32_e32 v134, 16, v154
	s_lshl_b64 s[30:31], s[0:1], 13
	v_cmp_lt_i32_e64 s[0:1], v134, v156
	v_cmp_eq_u32_e64 s[4:5], 0, v131
	v_xor_b32_e32 v131, 8, v154
	v_cndmask_b32_e64 v134, v154, v134, s[0:1]
	v_cmp_lt_i32_e64 s[0:1], v131, v156
	s_lshl_b32 s16, s14, 6
	v_and_b32_e32 v130, 63, v164
	v_cndmask_b32_e64 v131, v154, v131, s[0:1]
	v_lshlrev_b32_e32 v151, 2, v131
	v_xor_b32_e32 v131, 4, v154
	v_cmp_lt_i32_e64 s[0:1], v131, v156
	v_and_b32_e32 v133, 2, v164
	s_ashr_i32 s17, s16, 31
	v_cndmask_b32_e64 v131, v154, v131, s[0:1]
	v_lshlrev_b32_e32 v152, 2, v131
	v_xor_b32_e32 v131, 2, v154
	v_cmp_lt_i32_e64 s[0:1], v131, v156
	v_cmp_eq_u32_e64 s[12:13], 0, v130
	v_lshlrev_b32_e32 v130, 1, v167
	v_cndmask_b32_e64 v131, v154, v131, s[0:1]
	v_lshlrev_b32_e32 v153, 2, v131
	v_and_b32_e32 v131, 1, v164
	v_cmp_eq_u32_e64 s[10:11], 0, v131
	v_xor_b32_e32 v131, 1, v154
	v_cmp_lt_i32_e64 s[0:1], v131, v156
	v_lshl_or_b32 v140, v168, 2, v130
	v_lshlrev_b32_e32 v143, 7, v167
	v_cndmask_b32_e64 v131, v154, v131, s[0:1]
	s_lshr_b32 s0, s14, 4
	s_mul_hi_u32 s22, s0, 0x2100000
	s_mul_i32 s23, s0, 0x2100000
	v_cmp_lt_i32_e64 s[0:1], v155, v156
	v_lshl_add_u32 v167, v167, 2, s45
	v_lshlrev_b32_e32 v139, 2, v168
	v_lshlrev_b32_e32 v150, 2, v134
	v_cmp_eq_u32_e64 s[8:9], 0, v133
	v_lshl_or_b32 v166, v168, 4, v163
	v_lshl_add_u32 v168, v168, 3, v167
	s_waitcnt vmcnt(1)
	v_mul_f32_e32 v132, 0x3fb8aa3b, v132
	v_exp_f32_e32 v148, v132
	v_and_b32_e32 v132, 4, v164
	v_lshlrev_b32_e32 v164, 2, v131
	v_cndmask_b32_e64 v131, v154, v155, s[0:1]
	s_lshl_b64 s[0:1], s[36:37], 9
	s_add_u32 s0, s0, s15
	s_addc_u32 s1, s1, 0
	s_add_u32 s18, s39, s0
	s_addc_u32 s62, s40, s1
	s_lshl_b64 s[0:1], s[36:37], 14
	s_lshl_b64 s[16:17], s[16:17], 1
	s_add_u32 s0, s0, s16
	s_addc_u32 s1, s1, s17
	s_add_u32 s0, s41, s0
	s_addc_u32 s1, s42, s1
	v_lshl_add_u64 v[144:145], s[0:1], 0, v[140:141]
	s_lshl_b64 s[0:1], s[36:37], 13
	s_add_u32 s0, s23, s0
	s_addc_u32 s1, s22, s1
	s_and_b32 s14, s14, 15
	s_lshl_b32 s14, s14, 7
	s_or_b32 s0, s0, s14
	s_add_u32 s0, s43, s0
	s_addc_u32 s1, s44, s1
	v_cmp_eq_u32_e64 s[6:7], 0, v132
	v_lshlrev_b32_e32 v165, 2, v131
	v_lshl_add_u64 v[146:147], s[0:1], 0, v[140:141]
	global_load_ushort v210, v[146:147], off
	global_load_ushort v211, v[146:147], off offset:2048
	v_lshl_add_u64 v[214:215], v[146:147], 0, s[28:29]
	v_lshl_add_u64 v[214:215], v[214:215], 0, s[28:29]
	global_load_ushort v212, v[214:215], off
	global_load_ushort v213, v[214:215], off offset:2048
	s_mov_b64 s[0:1], 0
	s_mov_b32 s14, s82
	s_branch .LBB0_929

.LBB0_929:
	s_add_i32 s15, s14, 0
	v_mov_b32_e32 v130, s15
	ds_read_b32 v169, v130 offset:12288
	v_add_u32_e32 v177, 0, v167
	s_waitcnt lgkmcnt(0)
	v_mul_f32_e32 v130, v169, v148
	v_mul_f32_e32 v130, 0xbfb8aa3b, v130
	v_exp_f32_e32 v140, v130
	v_add_u32_e32 v130, 0, v166
	ds_read_b128 v[134:137], v130
	ds_read_b128 v[130:133], v130 offset:2048
	ds_read2_b32 v[170:171], v177 offset1:2
	ds_read2_b32 v[172:173], v177 offset0:4 offset1:6
	ds_read2_b32 v[178:179], v177 offset0:8 offset1:10
	ds_read2_b32 v[180:181], v177 offset0:12 offset1:14
	s_waitcnt lgkmcnt(3)
	v_mul_f32_e32 v170, v169, v170
	v_pk_mul_f32 v[182:183], v[136:137], v[170:171] op_sel_hi:[1,0]
	v_pk_mul_f32 v[184:185], v[134:135], v[170:171] op_sel_hi:[1,0]
	v_pk_fma_f32 v[92:93], v[92:93], v[140:141], v[182:183] op_sel_hi:[1,0,1]
	v_pk_fma_f32 v[90:91], v[90:91], v[140:141], v[184:185] op_sel_hi:[1,0,1]
	v_mul_f32_e32 v182, v133, v93
	v_mul_f32_e32 v170, v131, v91
	v_fmac_f32_e32 v170, v130, v90
	v_fmac_f32_e32 v182, v132, v92
	v_add_f32_e32 v184, v170, v182
	v_mul_f32_e32 v170, v169, v171
	v_pk_mul_f32 v[182:183], v[136:137], v[170:171] op_sel_hi:[1,0]
	v_pk_mul_f32 v[170:171], v[134:135], v[170:171] op_sel_hi:[1,0]
	v_pk_fma_f32 v[88:89], v[88:89], v[140:141], v[182:183] op_sel_hi:[1,0,1]
	v_pk_fma_f32 v[86:87], v[86:87], v[140:141], v[170:171] op_sel_hi:[1,0,1]
	v_mul_f32_e32 v171, v133, v89
	v_mul_f32_e32 v170, v131, v87
	v_fmac_f32_e32 v170, v130, v86
	v_fmac_f32_e32 v171, v132, v88
	v_add_f32_e32 v185, v170, v171
	s_waitcnt lgkmcnt(2)
	v_mul_f32_e32 v170, v169, v172
	v_pk_mul_f32 v[182:183], v[136:137], v[170:171] op_sel_hi:[1,0]
	v_pk_mul_f32 v[170:171], v[134:135], v[170:171] op_sel_hi:[1,0]
	v_pk_fma_f32 v[84:85], v[84:85], v[140:141], v[182:183] op_sel_hi:[1,0,1]
	v_pk_fma_f32 v[82:83], v[82:83], v[140:141], v[170:171] op_sel_hi:[1,0,1]
	v_mul_f32_e32 v171, v133, v85
	v_mul_f32_e32 v170, v131, v83
	v_fmac_f32_e32 v170, v130, v82
	v_fmac_f32_e32 v171, v132, v84
	v_add_f32_e32 v182, v170, v171
	v_mul_f32_e32 v170, v169, v173
	v_pk_mul_f32 v[172:173], v[136:137], v[170:171] op_sel_hi:[1,0]
	v_pk_mul_f32 v[170:171], v[134:135], v[170:171] op_sel_hi:[1,0]
	v_pk_fma_f32 v[80:81], v[80:81], v[140:141], v[172:173] op_sel_hi:[1,0,1]
	v_pk_fma_f32 v[78:79], v[78:79], v[140:141], v[170:171] op_sel_hi:[1,0,1]
	v_mul_f32_e32 v171, v133, v81
	v_mul_f32_e32 v170, v131, v79
	v_fmac_f32_e32 v170, v130, v78
	v_fmac_f32_e32 v171, v132, v80
	v_add_f32_e32 v183, v170, v171
	s_waitcnt lgkmcnt(1)
	v_mul_f32_e32 v170, v169, v178
	v_pk_mul_f32 v[172:173], v[136:137], v[170:171] op_sel_hi:[1,0]
	v_pk_mul_f32 v[170:171], v[134:135], v[170:171] op_sel_hi:[1,0]
	v_pk_fma_f32 v[128:129], v[128:129], v[140:141], v[172:173] op_sel_hi:[1,0,1]
	v_pk_fma_f32 v[126:127], v[126:127], v[140:141], v[170:171] op_sel_hi:[1,0,1]
	v_mul_f32_e32 v171, v133, v129
	v_mul_f32_e32 v170, v131, v127
	v_fmac_f32_e32 v170, v130, v126
	v_fmac_f32_e32 v171, v132, v128
	v_add_f32_e32 v186, v170, v171
	v_mul_f32_e32 v170, v169, v179
	v_pk_mul_f32 v[172:173], v[136:137], v[170:171] op_sel_hi:[1,0]
	v_pk_mul_f32 v[170:171], v[134:135], v[170:171] op_sel_hi:[1,0]
	v_pk_fma_f32 v[76:77], v[76:77], v[140:141], v[172:173] op_sel_hi:[1,0,1]
	v_pk_fma_f32 v[74:75], v[74:75], v[140:141], v[170:171] op_sel_hi:[1,0,1]
	v_mul_f32_e32 v171, v133, v77
	v_mul_f32_e32 v170, v131, v75
	v_fmac_f32_e32 v170, v130, v74
	v_fmac_f32_e32 v171, v132, v76
	v_add_f32_e32 v187, v170, v171
	s_waitcnt lgkmcnt(0)
	v_mul_f32_e32 v170, v169, v180
	v_pk_mul_f32 v[172:173], v[136:137], v[170:171] op_sel_hi:[1,0]
	v_pk_mul_f32 v[170:171], v[134:135], v[170:171] op_sel_hi:[1,0]
	v_pk_fma_f32 v[72:73], v[72:73], v[140:141], v[172:173] op_sel_hi:[1,0,1]
	v_pk_fma_f32 v[70:71], v[70:71], v[140:141], v[170:171] op_sel_hi:[1,0,1]
	v_mul_f32_e32 v171, v133, v73
	v_mul_f32_e32 v170, v131, v71
	v_fmac_f32_e32 v170, v130, v70
	v_fmac_f32_e32 v171, v132, v72
	v_add_f32_e32 v180, v170, v171
	v_mul_f32_e32 v170, v169, v181
	v_pk_mul_f32 v[172:173], v[136:137], v[170:171] op_sel_hi:[1,0]
	v_pk_mul_f32 v[170:171], v[134:135], v[170:171] op_sel_hi:[1,0]
	v_pk_fma_f32 v[124:125], v[124:125], v[140:141], v[172:173] op_sel_hi:[1,0,1]
	v_pk_fma_f32 v[122:123], v[122:123], v[140:141], v[170:171] op_sel_hi:[1,0,1]
	v_mul_f32_e32 v171, v133, v125
	v_mul_f32_e32 v170, v131, v123
	v_fmac_f32_e32 v170, v130, v122
	v_fmac_f32_e32 v171, v132, v124
	v_add_f32_e32 v181, v170, v171
	ds_read2_b32 v[170:171], v177 offset0:16 offset1:18
	s_waitcnt lgkmcnt(0)
	v_mul_f32_e32 v170, v169, v170
	v_pk_mul_f32 v[172:173], v[136:137], v[170:171] op_sel_hi:[1,0]
	v_pk_mul_f32 v[178:179], v[134:135], v[170:171] op_sel_hi:[1,0]
	v_pk_fma_f32 v[68:69], v[68:69], v[140:141], v[172:173] op_sel_hi:[1,0,1]
	v_pk_fma_f32 v[66:67], v[66:67], v[140:141], v[178:179] op_sel_hi:[1,0,1]
	v_mul_f32_e32 v172, v133, v69
	v_mul_f32_e32 v170, v131, v67
	v_fmac_f32_e32 v170, v130, v66
	v_fmac_f32_e32 v172, v132, v68
	v_add_f32_e32 v188, v170, v172
	v_mul_f32_e32 v170, v169, v171
	v_pk_mul_f32 v[172:173], v[136:137], v[170:171] op_sel_hi:[1,0]
	v_pk_mul_f32 v[170:171], v[134:135], v[170:171] op_sel_hi:[1,0]
	v_pk_fma_f32 v[64:65], v[64:65], v[140:141], v[172:173] op_sel_hi:[1,0,1]
	v_pk_fma_f32 v[62:63], v[62:63], v[140:141], v[170:171] op_sel_hi:[1,0,1]
	v_mul_f32_e32 v171, v133, v65
	v_mul_f32_e32 v170, v131, v63
	v_fmac_f32_e32 v170, v130, v62
	v_fmac_f32_e32 v171, v132, v64
	v_add_f32_e32 v189, v170, v171
	ds_read2_b32 v[170:171], v177 offset0:20 offset1:22
	s_waitcnt lgkmcnt(0)
	v_mul_f32_e32 v170, v169, v170
	v_pk_mul_f32 v[172:173], v[136:137], v[170:171] op_sel_hi:[1,0]
	v_pk_mul_f32 v[178:179], v[134:135], v[170:171] op_sel_hi:[1,0]
	v_pk_fma_f32 v[60:61], v[60:61], v[140:141], v[172:173] op_sel_hi:[1,0,1]
	v_pk_fma_f32 v[58:59], v[58:59], v[140:141], v[178:179] op_sel_hi:[1,0,1]
	v_mul_f32_e32 v172, v133, v61
	v_mul_f32_e32 v170, v131, v59
	v_fmac_f32_e32 v170, v130, v58
	v_fmac_f32_e32 v172, v132, v60
	v_add_f32_e32 v190, v170, v172
	v_mul_f32_e32 v170, v169, v171
	v_pk_mul_f32 v[172:173], v[136:137], v[170:171] op_sel_hi:[1,0]
	v_pk_mul_f32 v[170:171], v[134:135], v[170:171] op_sel_hi:[1,0]
	v_pk_fma_f32 v[56:57], v[56:57], v[140:141], v[172:173] op_sel_hi:[1,0,1]
	v_pk_fma_f32 v[54:55], v[54:55], v[140:141], v[170:171] op_sel_hi:[1,0,1]
	v_mul_f32_e32 v171, v133, v57
	v_mul_f32_e32 v170, v131, v55
	v_fmac_f32_e32 v170, v130, v54
	v_fmac_f32_e32 v171, v132, v56
	v_add_f32_e32 v191, v170, v171
	ds_read2_b32 v[170:171], v177 offset0:24 offset1:26
	s_waitcnt lgkmcnt(0)
	v_mul_f32_e32 v170, v169, v170
	v_pk_mul_f32 v[172:173], v[136:137], v[170:171] op_sel_hi:[1,0]
	v_pk_mul_f32 v[178:179], v[134:135], v[170:171] op_sel_hi:[1,0]
	v_pk_fma_f32 v[108:109], v[108:109], v[140:141], v[172:173] op_sel_hi:[1,0,1]
	v_pk_fma_f32 v[106:107], v[106:107], v[140:141], v[178:179] op_sel_hi:[1,0,1]
	v_mul_f32_e32 v172, v133, v109
	v_mul_f32_e32 v170, v131, v107
	v_fmac_f32_e32 v170, v130, v106
	v_fmac_f32_e32 v172, v132, v108
	v_add_f32_e32 v192, v170, v172
	v_mul_f32_e32 v170, v169, v171
	v_pk_mul_f32 v[172:173], v[136:137], v[170:171] op_sel_hi:[1,0]
	v_pk_mul_f32 v[170:171], v[134:135], v[170:171] op_sel_hi:[1,0]
	v_pk_fma_f32 v[28:29], v[28:29], v[140:141], v[172:173] op_sel_hi:[1,0,1]
	v_pk_fma_f32 v[26:27], v[26:27], v[140:141], v[170:171] op_sel_hi:[1,0,1]
	v_mul_f32_e32 v171, v133, v29
	v_mul_f32_e32 v170, v131, v27
	v_fmac_f32_e32 v170, v130, v26
	v_fmac_f32_e32 v171, v132, v28
	v_add_f32_e32 v193, v170, v171
	ds_read2_b32 v[170:171], v177 offset0:28 offset1:30
	s_waitcnt lgkmcnt(0)
	v_mul_f32_e32 v170, v169, v170
	v_pk_mul_f32 v[172:173], v[136:137], v[170:171] op_sel_hi:[1,0]
	v_pk_mul_f32 v[178:179], v[134:135], v[170:171] op_sel_hi:[1,0]
	v_pk_fma_f32 v[24:25], v[24:25], v[140:141], v[172:173] op_sel_hi:[1,0,1]
	v_pk_fma_f32 v[22:23], v[22:23], v[140:141], v[178:179] op_sel_hi:[1,0,1]
	v_mul_f32_e32 v172, v133, v25
	v_mul_f32_e32 v170, v131, v23
	v_fmac_f32_e32 v170, v130, v22
	v_fmac_f32_e32 v172, v132, v24
	v_add_f32_e32 v194, v170, v172
	v_mul_f32_e32 v170, v169, v171
	v_pk_mul_f32 v[172:173], v[136:137], v[170:171] op_sel_hi:[1,0]
	v_pk_mul_f32 v[170:171], v[134:135], v[170:171] op_sel_hi:[1,0]
	v_pk_fma_f32 v[20:21], v[20:21], v[140:141], v[172:173] op_sel_hi:[1,0,1]
	v_pk_fma_f32 v[18:19], v[18:19], v[140:141], v[170:171] op_sel_hi:[1,0,1]
	v_mul_f32_e32 v171, v133, v21
	v_mul_f32_e32 v170, v131, v19
	v_fmac_f32_e32 v170, v130, v18
	v_fmac_f32_e32 v171, v132, v20
	v_add_f32_e32 v195, v170, v171
	ds_read2_b32 v[170:171], v177 offset0:32 offset1:34
	s_waitcnt lgkmcnt(0)
	v_mul_f32_e32 v170, v169, v170
	v_pk_mul_f32 v[172:173], v[136:137], v[170:171] op_sel_hi:[1,0]
	v_pk_mul_f32 v[178:179], v[134:135], v[170:171] op_sel_hi:[1,0]
	v_pk_fma_f32 v[52:53], v[52:53], v[140:141], v[172:173] op_sel_hi:[1,0,1]
	v_pk_fma_f32 v[50:51], v[50:51], v[140:141], v[178:179] op_sel_hi:[1,0,1]
	v_mul_f32_e32 v172, v133, v53
	v_mul_f32_e32 v170, v131, v51
	v_fmac_f32_e32 v170, v130, v50
	v_fmac_f32_e32 v172, v132, v52
	v_add_f32_e32 v196, v170, v172
	v_mul_f32_e32 v170, v169, v171
	v_pk_mul_f32 v[172:173], v[136:137], v[170:171] op_sel_hi:[1,0]
	v_pk_mul_f32 v[170:171], v[134:135], v[170:171] op_sel_hi:[1,0]
	v_pk_fma_f32 v[48:49], v[48:49], v[140:141], v[172:173] op_sel_hi:[1,0,1]
	v_pk_fma_f32 v[46:47], v[46:47], v[140:141], v[170:171] op_sel_hi:[1,0,1]
	v_mul_f32_e32 v171, v133, v49
	v_mul_f32_e32 v170, v131, v47
	v_fmac_f32_e32 v170, v130, v46
	v_fmac_f32_e32 v171, v132, v48
	v_add_f32_e32 v197, v170, v171
	ds_read2_b32 v[170:171], v177 offset0:36 offset1:38
	s_waitcnt lgkmcnt(0)
	v_mul_f32_e32 v170, v169, v170
	v_pk_mul_f32 v[172:173], v[136:137], v[170:171] op_sel_hi:[1,0]
	v_pk_mul_f32 v[178:179], v[134:135], v[170:171] op_sel_hi:[1,0]
	v_pk_fma_f32 v[44:45], v[44:45], v[140:141], v[172:173] op_sel_hi:[1,0,1]
	v_pk_fma_f32 v[42:43], v[42:43], v[140:141], v[178:179] op_sel_hi:[1,0,1]
	v_mul_f32_e32 v172, v133, v45
	v_mul_f32_e32 v170, v131, v43
	v_fmac_f32_e32 v170, v130, v42
	v_fmac_f32_e32 v172, v132, v44
	v_add_f32_e32 v198, v170, v172
	v_mul_f32_e32 v170, v169, v171
	v_pk_mul_f32 v[172:173], v[136:137], v[170:171] op_sel_hi:[1,0]
	v_pk_mul_f32 v[170:171], v[134:135], v[170:171] op_sel_hi:[1,0]
	v_pk_fma_f32 v[116:117], v[116:117], v[140:141], v[172:173] op_sel_hi:[1,0,1]
	v_pk_fma_f32 v[114:115], v[114:115], v[140:141], v[170:171] op_sel_hi:[1,0,1]
	v_mul_f32_e32 v171, v133, v117
	v_mul_f32_e32 v170, v131, v115
	v_fmac_f32_e32 v170, v130, v114
	v_fmac_f32_e32 v171, v132, v116
	v_add_f32_e32 v199, v170, v171
	ds_read2_b32 v[170:171], v177 offset0:40 offset1:42
	s_waitcnt lgkmcnt(0)
	v_mul_f32_e32 v170, v169, v170
	v_pk_mul_f32 v[172:173], v[136:137], v[170:171] op_sel_hi:[1,0]
	v_pk_mul_f32 v[178:179], v[134:135], v[170:171] op_sel_hi:[1,0]
	v_pk_fma_f32 v[16:17], v[16:17], v[140:141], v[172:173] op_sel_hi:[1,0,1]
	v_pk_fma_f32 v[14:15], v[14:15], v[140:141], v[178:179] op_sel_hi:[1,0,1]
	v_mul_f32_e32 v172, v133, v17
	v_mul_f32_e32 v170, v131, v15
	v_fmac_f32_e32 v170, v130, v14
	v_fmac_f32_e32 v172, v132, v16
	v_add_f32_e32 v200, v170, v172
	v_mul_f32_e32 v170, v169, v171
	v_pk_mul_f32 v[172:173], v[136:137], v[170:171] op_sel_hi:[1,0]
	v_pk_mul_f32 v[170:171], v[134:135], v[170:171] op_sel_hi:[1,0]
	v_pk_fma_f32 v[12:13], v[12:13], v[140:141], v[172:173] op_sel_hi:[1,0,1]
	v_pk_fma_f32 v[10:11], v[10:11], v[140:141], v[170:171] op_sel_hi:[1,0,1]
	v_mul_f32_e32 v171, v133, v13
	v_mul_f32_e32 v170, v131, v11
	v_fmac_f32_e32 v170, v130, v10
	v_fmac_f32_e32 v171, v132, v12
	v_add_f32_e32 v201, v170, v171
	ds_read2_b32 v[170:171], v177 offset0:44 offset1:46
	s_waitcnt lgkmcnt(0)
	v_mul_f32_e32 v170, v169, v170
	v_pk_mul_f32 v[172:173], v[136:137], v[170:171] op_sel_hi:[1,0]
	v_pk_mul_f32 v[178:179], v[134:135], v[170:171] op_sel_hi:[1,0]
	v_pk_fma_f32 v[8:9], v[8:9], v[140:141], v[172:173] op_sel_hi:[1,0,1]
	v_pk_fma_f32 v[6:7], v[6:7], v[140:141], v[178:179] op_sel_hi:[1,0,1]
	v_mul_f32_e32 v172, v133, v9
	v_mul_f32_e32 v170, v131, v7
	v_fmac_f32_e32 v170, v130, v6
	v_fmac_f32_e32 v172, v132, v8
	v_add_f32_e32 v202, v170, v172
	v_mul_f32_e32 v170, v169, v171
	v_pk_mul_f32 v[172:173], v[136:137], v[170:171] op_sel_hi:[1,0]
	v_pk_mul_f32 v[170:171], v[134:135], v[170:171] op_sel_hi:[1,0]
	v_pk_fma_f32 v[120:121], v[120:121], v[140:141], v[172:173] op_sel_hi:[1,0,1]
	v_pk_fma_f32 v[118:119], v[118:119], v[140:141], v[170:171] op_sel_hi:[1,0,1]
	v_mul_f32_e32 v171, v133, v121
	v_mul_f32_e32 v170, v131, v119
	v_fmac_f32_e32 v170, v130, v118
	v_fmac_f32_e32 v171, v132, v120
	v_add_f32_e32 v203, v170, v171
	ds_read2_b32 v[170:171], v177 offset0:48 offset1:50
	s_waitcnt lgkmcnt(0)
	v_mul_f32_e32 v170, v169, v170
	v_pk_mul_f32 v[172:173], v[136:137], v[170:171] op_sel_hi:[1,0]
	v_pk_mul_f32 v[178:179], v[134:135], v[170:171] op_sel_hi:[1,0]
	v_pk_fma_f32 v[4:5], v[4:5], v[140:141], v[172:173] op_sel_hi:[1,0,1]
	v_pk_fma_f32 v[2:3], v[2:3], v[140:141], v[178:179] op_sel_hi:[1,0,1]
	v_mul_f32_e32 v172, v133, v5
	v_mul_f32_e32 v170, v131, v3
	v_fmac_f32_e32 v170, v130, v2
	v_fmac_f32_e32 v172, v132, v4
	v_add_f32_e32 v204, v170, v172
	v_mul_f32_e32 v170, v169, v171
	v_pk_mul_f32 v[172:173], v[136:137], v[170:171] op_sel_hi:[1,0]
	v_pk_mul_f32 v[170:171], v[134:135], v[170:171] op_sel_hi:[1,0]
	v_pk_fma_f32 v[32:33], v[32:33], v[140:141], v[172:173] op_sel_hi:[1,0,1]
	v_pk_fma_f32 v[30:31], v[30:31], v[140:141], v[170:171] op_sel_hi:[1,0,1]
	v_mul_f32_e32 v171, v133, v33
	v_mul_f32_e32 v170, v131, v31
	v_fmac_f32_e32 v170, v130, v30
	v_fmac_f32_e32 v171, v132, v32
	v_add_f32_e32 v205, v170, v171
	ds_read2_b32 v[170:171], v177 offset0:52 offset1:54
	s_waitcnt lgkmcnt(0)
	v_mul_f32_e32 v170, v169, v170
	v_pk_mul_f32 v[172:173], v[136:137], v[170:171] op_sel_hi:[1,0]
	v_pk_mul_f32 v[178:179], v[134:135], v[170:171] op_sel_hi:[1,0]
	v_pk_fma_f32 v[36:37], v[36:37], v[140:141], v[172:173] op_sel_hi:[1,0,1]
	v_pk_fma_f32 v[34:35], v[34:35], v[140:141], v[178:179] op_sel_hi:[1,0,1]
	v_mul_f32_e32 v172, v133, v37
	v_mul_f32_e32 v170, v131, v35
	v_fmac_f32_e32 v170, v130, v34
	v_fmac_f32_e32 v172, v132, v36
	v_add_f32_e32 v206, v170, v172
	v_mul_f32_e32 v170, v169, v171
	v_pk_mul_f32 v[172:173], v[136:137], v[170:171] op_sel_hi:[1,0]
	v_pk_mul_f32 v[170:171], v[134:135], v[170:171] op_sel_hi:[1,0]
	v_pk_fma_f32 v[40:41], v[40:41], v[140:141], v[172:173] op_sel_hi:[1,0,1]
	v_pk_fma_f32 v[38:39], v[38:39], v[140:141], v[170:171] op_sel_hi:[1,0,1]
	v_mul_f32_e32 v171, v133, v41
	v_mul_f32_e32 v170, v131, v39
	v_fmac_f32_e32 v170, v130, v38
	v_fmac_f32_e32 v171, v132, v40
	v_add_f32_e32 v207, v170, v171
	ds_read2_b32 v[170:171], v177 offset0:56 offset1:58
	s_waitcnt lgkmcnt(0)
	v_mul_f32_e32 v170, v169, v170
	v_pk_mul_f32 v[172:173], v[136:137], v[170:171] op_sel_hi:[1,0]
	v_pk_mul_f32 v[178:179], v[134:135], v[170:171] op_sel_hi:[1,0]
	v_pk_fma_f32 v[96:97], v[96:97], v[140:141], v[172:173] op_sel_hi:[1,0,1]
	v_pk_fma_f32 v[94:95], v[94:95], v[140:141], v[178:179] op_sel_hi:[1,0,1]
	v_mul_f32_e32 v172, v133, v97
	v_mul_f32_e32 v170, v131, v95
	v_fmac_f32_e32 v170, v130, v94
	v_fmac_f32_e32 v172, v132, v96
	v_add_f32_e32 v208, v170, v172
	v_mul_f32_e32 v170, v169, v171
	v_pk_mul_f32 v[172:173], v[136:137], v[170:171] op_sel_hi:[1,0]
	v_pk_mul_f32 v[170:171], v[134:135], v[170:171] op_sel_hi:[1,0]
	v_pk_fma_f32 v[100:101], v[100:101], v[140:141], v[172:173] op_sel_hi:[1,0,1]
	v_pk_fma_f32 v[98:99], v[98:99], v[140:141], v[170:171] op_sel_hi:[1,0,1]
	v_mul_f32_e32 v171, v133, v101
	v_mul_f32_e32 v170, v131, v99
	v_fmac_f32_e32 v170, v130, v98
	v_fmac_f32_e32 v171, v132, v100
	v_add_f32_e32 v209, v170, v171
	ds_read2_b32 v[170:171], v177 offset0:60 offset1:62
	v_cndmask_b32_e32 v177, v191, v207, vcc
	ds_bpermute_b32 v177, v150, v177
	s_waitcnt lgkmcnt(1)
	v_mul_f32_e32 v170, v169, v170
	v_pk_mul_f32 v[172:173], v[136:137], v[170:171] op_sel_hi:[1,0]
	v_pk_mul_f32 v[178:179], v[134:135], v[170:171] op_sel_hi:[1,0]
	v_pk_fma_f32 v[104:105], v[104:105], v[140:141], v[172:173] op_sel_hi:[1,0,1]
	v_pk_fma_f32 v[102:103], v[102:103], v[140:141], v[178:179] op_sel_hi:[1,0,1]
	v_mul_f32_e32 v172, v133, v105
	v_mul_f32_e32 v170, v131, v103
	v_fmac_f32_e32 v170, v130, v102
	v_fmac_f32_e32 v172, v132, v104
	v_add_f32_e32 v172, v170, v172
	v_mul_f32_e32 v170, v169, v171
	v_pk_mul_f32 v[134:135], v[134:135], v[170:171] op_sel_hi:[1,0]
	v_pk_mul_f32 v[136:137], v[136:137], v[170:171] op_sel_hi:[1,0]
	v_pk_fma_f32 v[110:111], v[110:111], v[140:141], v[134:135] op_sel_hi:[1,0,1]
	v_pk_fma_f32 v[112:113], v[112:113], v[140:141], v[136:137] op_sel_hi:[1,0,1]
	v_mul_f32_e32 v131, v131, v111
	v_fmac_f32_e32 v131, v130, v110
	v_mul_f32_e32 v130, v133, v113
	v_fmac_f32_e32 v130, v132, v112
	v_cndmask_b32_e32 v132, v184, v196, vcc
	ds_bpermute_b32 v132, v150, v132
	v_cndmask_b32_e32 v133, v185, v197, vcc
	ds_bpermute_b32 v133, v150, v133
	v_cndmask_b32_e32 v134, v182, v198, vcc
	ds_bpermute_b32 v134, v150, v134
	v_cndmask_b32_e32 v135, v183, v199, vcc
	ds_bpermute_b32 v135, v150, v135
	v_cndmask_b32_e32 v136, v186, v200, vcc
	v_add_f32_e32 v130, v131, v130
	v_cndmask_b32_e32 v131, v196, v184, vcc
	ds_bpermute_b32 v136, v150, v136
	v_cndmask_b32_e32 v137, v187, v201, vcc
	s_waitcnt lgkmcnt(4)
	v_add_f32_e32 v131, v131, v132
	v_cndmask_b32_e32 v132, v197, v185, vcc
	ds_bpermute_b32 v137, v150, v137
	v_cndmask_b32_e32 v140, v180, v202, vcc
	s_waitcnt lgkmcnt(4)
	v_add_f32_e32 v132, v132, v133
	v_cndmask_b32_e32 v133, v198, v182, vcc
	ds_bpermute_b32 v140, v150, v140
	v_cndmask_b32_e32 v169, v181, v203, vcc
	s_waitcnt lgkmcnt(4)
	v_add_f32_e32 v133, v133, v134
	v_cndmask_b32_e32 v134, v199, v183, vcc
	ds_bpermute_b32 v169, v150, v169
	v_cndmask_b32_e32 v170, v188, v204, vcc
	s_waitcnt lgkmcnt(4)
	v_add_f32_e32 v134, v134, v135
	v_cndmask_b32_e32 v135, v200, v186, vcc
	ds_bpermute_b32 v170, v150, v170
	v_cndmask_b32_e32 v171, v189, v205, vcc
	s_waitcnt lgkmcnt(4)
	v_add_f32_e32 v135, v135, v136
	v_cndmask_b32_e32 v136, v201, v187, vcc
	ds_bpermute_b32 v171, v150, v171
	v_cndmask_b32_e32 v173, v190, v206, vcc
	s_waitcnt lgkmcnt(4)
	v_add_f32_e32 v136, v136, v137
	v_cndmask_b32_e32 v137, v202, v180, vcc
	ds_bpermute_b32 v173, v150, v173
	s_waitcnt lgkmcnt(4)
	v_add_f32_e32 v137, v137, v140
	v_cndmask_b32_e32 v140, v203, v181, vcc
	v_cndmask_b32_e32 v178, v192, v208, vcc
	s_waitcnt lgkmcnt(3)
	v_add_f32_e32 v140, v140, v169
	v_cndmask_b32_e32 v169, v204, v188, vcc
	ds_bpermute_b32 v178, v150, v178
	v_cndmask_b32_e32 v179, v193, v209, vcc
	s_waitcnt lgkmcnt(3)
	v_add_f32_e32 v169, v169, v170
	v_cndmask_b32_e32 v170, v205, v189, vcc
	ds_bpermute_b32 v179, v150, v179
	s_waitcnt lgkmcnt(3)
	v_add_f32_e32 v170, v170, v171
	v_cndmask_b32_e32 v171, v206, v190, vcc
	s_waitcnt lgkmcnt(2)
	v_add_f32_e32 v171, v171, v173
	v_cndmask_b32_e32 v173, v207, v191, vcc
	v_add_f32_e32 v173, v173, v177
	v_cndmask_b32_e32 v177, v208, v192, vcc
	s_waitcnt lgkmcnt(1)
	v_add_f32_e32 v177, v177, v178
	v_cndmask_b32_e32 v178, v209, v193, vcc
	s_waitcnt lgkmcnt(0)
	v_add_f32_e32 v178, v178, v179
	v_cndmask_b32_e32 v179, v172, v194, vcc
	v_cndmask_b32_e32 v172, v194, v172, vcc
	ds_bpermute_b32 v172, v150, v172
	s_waitcnt lgkmcnt(0)
	v_add_f32_e32 v172, v179, v172
	v_cndmask_b32_e32 v179, v130, v195, vcc
	v_cndmask_b32_e32 v130, v195, v130, vcc
	ds_bpermute_b32 v130, v150, v130
	s_waitcnt lgkmcnt(0)
	v_add_f32_e32 v130, v179, v130
	v_cndmask_b32_e64 v179, v169, v131, s[4:5]
	v_cndmask_b32_e64 v131, v131, v169, s[4:5]
	v_cndmask_b32_e64 v169, v170, v132, s[4:5]
	v_cndmask_b32_e64 v132, v132, v170, s[4:5]
	ds_bpermute_b32 v132, v151, v132
	ds_bpermute_b32 v131, v151, v131
	s_waitcnt lgkmcnt(1)
	v_add_f32_e32 v132, v169, v132
	v_cndmask_b32_e64 v169, v171, v133, s[4:5]
	v_cndmask_b32_e64 v133, v133, v171, s[4:5]
	ds_bpermute_b32 v133, v151, v133
	s_waitcnt lgkmcnt(1)
	v_add_f32_e32 v131, v179, v131
	s_waitcnt lgkmcnt(0)
	v_add_f32_e32 v133, v169, v133
	v_cndmask_b32_e64 v169, v173, v134, s[4:5]
	v_cndmask_b32_e64 v134, v134, v173, s[4:5]
	ds_bpermute_b32 v134, v151, v134
	s_waitcnt lgkmcnt(0)
	v_add_f32_e32 v134, v169, v134
	v_cndmask_b32_e64 v169, v177, v135, s[4:5]
	v_cndmask_b32_e64 v135, v135, v177, s[4:5]
	ds_bpermute_b32 v135, v151, v135
	s_waitcnt lgkmcnt(0)
	v_add_f32_e32 v135, v169, v135
	v_cndmask_b32_e64 v169, v178, v136, s[4:5]
	v_cndmask_b32_e64 v136, v136, v178, s[4:5]
	ds_bpermute_b32 v136, v151, v136
	s_waitcnt lgkmcnt(0)
	v_add_f32_e32 v136, v169, v136
	v_cndmask_b32_e64 v169, v172, v137, s[4:5]
	v_cndmask_b32_e64 v137, v137, v172, s[4:5]
	ds_bpermute_b32 v137, v151, v137
	s_waitcnt lgkmcnt(0)
	v_add_f32_e32 v137, v169, v137
	v_cndmask_b32_e64 v169, v130, v140, s[4:5]
	v_cndmask_b32_e64 v130, v140, v130, s[4:5]
	v_cndmask_b32_e64 v140, v135, v131, s[6:7]
	v_cndmask_b32_e64 v131, v131, v135, s[6:7]
	v_cndmask_b32_e64 v135, v136, v132, s[6:7]
	v_cndmask_b32_e64 v132, v132, v136, s[6:7]
	ds_bpermute_b32 v132, v152, v132
	ds_bpermute_b32 v130, v151, v130
	ds_bpermute_b32 v131, v152, v131
	s_waitcnt lgkmcnt(2)
	v_add_f32_e32 v132, v135, v132
	v_cndmask_b32_e64 v135, v137, v133, s[6:7]
	v_cndmask_b32_e64 v133, v133, v137, s[6:7]
	ds_bpermute_b32 v133, v152, v133
	s_waitcnt lgkmcnt(2)
	v_add_f32_e32 v130, v169, v130
	s_waitcnt lgkmcnt(1)
	v_add_f32_e32 v131, v140, v131
	s_waitcnt lgkmcnt(0)
	v_add_f32_e32 v133, v135, v133
	v_cndmask_b32_e64 v135, v130, v134, s[6:7]
	v_cndmask_b32_e64 v130, v134, v130, s[6:7]
	ds_bpermute_b32 v130, v152, v130
	v_cndmask_b32_e64 v134, v133, v131, s[8:9]
	v_cndmask_b32_e64 v131, v131, v133, s[8:9]
	ds_bpermute_b32 v131, v153, v131
	s_waitcnt lgkmcnt(1)
	v_add_f32_e32 v130, v135, v130
	v_cndmask_b32_e64 v133, v130, v132, s[8:9]
	v_cndmask_b32_e64 v130, v132, v130, s[8:9]
	ds_bpermute_b32 v130, v153, v130
	s_waitcnt lgkmcnt(1)
	v_add_f32_e32 v131, v134, v131
	s_waitcnt lgkmcnt(0)
	v_add_f32_e32 v130, v133, v130
	v_cndmask_b32_e64 v132, v130, v131, s[10:11]
	v_cndmask_b32_e64 v130, v131, v130, s[10:11]
	ds_bpermute_b32 v130, v164, v130
	v_add_u32_e32 v131, 0, v168
	ds_read_b32 v131, v131
	s_waitcnt lgkmcnt(1)
	v_add_f32_e32 v130, v132, v130
	s_waitcnt vmcnt(0) lgkmcnt(0)
	v_fmac_f32_e32 v130, v149, v131
	v_lshlrev_b32_e32 v131, 16, v210
	v_mov_b32_e32 v210, v211
	v_mov_b32_e32 v211, v212
	v_mov_b32_e32 v212, v213
	v_mul_f32_e32 v132, 0xbfb8aa3b, v131
	v_exp_f32_e32 v132, v132
	s_nop 0
	v_add_f32_e32 v132, 1.0, v132
	v_rcp_f32_e32 v132, v132
	s_nop 0
	v_mul_f32_e32 v131, v132, v131
	v_mul_f32_e32 v130, v130, v131
	v_cvt_pk_bf16_f32 v131, v130, s0
	global_store_short v[144:145], v131, off
	v_mul_f32_e32 v131, v130, v130
	ds_bpermute_b32 v131, v164, v131
	s_waitcnt lgkmcnt(0)
	v_fmac_f32_e32 v131, v130, v130
	ds_bpermute_b32 v130, v153, v131
	s_waitcnt lgkmcnt(0)
	v_add_f32_e32 v130, v131, v130
	ds_bpermute_b32 v131, v152, v130
	s_waitcnt lgkmcnt(0)
	v_add_f32_e32 v130, v130, v131
	ds_bpermute_b32 v131, v151, v130
	s_waitcnt lgkmcnt(0)
	v_add_f32_e32 v130, v130, v131
	ds_bpermute_b32 v131, v150, v130
	s_waitcnt lgkmcnt(0)
	v_add_f32_e32 v130, v130, v131
	ds_bpermute_b32 v131, v165, v130
	s_and_saveexec_b64 s[34:35], s[12:13]
	s_cbranch_execz .LBB0_928
	s_add_u32 s16, s18, s0
	s_addc_u32 s17, s62, s1
	s_waitcnt lgkmcnt(0)
	v_add_f32_e32 v130, v130, v131
	global_store_dword v141, v130, s[16:17]
	s_branch .LBB0_928
